# attention: DMA-offset slot addresses held in VGPRs; next-trip K address arithmetic fills the MFMA-result pad slots
# speedup vs baseline: 1.0048x; 1.0048x over previous
; #define LAS __attribute__((address_space(3)))
; __device__ __forceinline__ int otid() { int t = threadIdx.x; asm volatile("" : "+v"(t)); return t; }
; #define WBAR() do { asm volatile("s_waitcnt vmcnt(0) lgkmcnt(0)" ::: "memory"); __builtin_amdgcn_s_barrier(); asm volatile("" ::: "memory"); } while (0)
; __device__ __forceinline__ void attn_unit(const unsigned char* __restrict__ Qb, const unsigned char* __restrict__ Kh, const unsigned char* __restrict__ VTh, f16* __restrict__ Ob, int seq, LAS char* lds) {
;     const int tid = otid(), wid = __builtin_amdgcn_readfirstlane(tid >> 6), lane = tid & 63, r32 = lane & 31, hi = lane >> 5;
;     LAS float* ws = (LAS float*)(lds + WS8) + wid * 64; LAS float* li_l = ws; LAS float* al_l = ws + 32;
;     f32x16 o[5] = {}; v8i qf[3]; f32x16 negm;
; #pragma unroll
;     for (int r = 0; r < 16; ++r) negm[r] = SH;
;     const unsigned char* Qw = Qb + (long)(wid * 32 + r32) * LDQ + hi * 32;
; #pragma unroll
;     for (int st = 0; st < 3; ++st) { const v4i x = *(const v4i*)(Qw + 64 * st), y = *(const v4i*)(Qw + 64 * st + 16); qf[st] = (v8i){x[0], x[1], x[2], x[3], y[0], y[1], y[2], y[3]}; }
;     const int sw = (r32 >> 2) & 3;
;     const int ka0 = r32 * 192 + (((2 * hi) ^ sw) << 4), ka1 = r32 * 192 + (((2 * hi + 1) ^ sw) << 4);
;     const int va0 = r32 * 64 + (((2 * hi) ^ sw) << 4), va1 = r32 * 64 + (((2 * hi + 1) ^ sw) << 4);
;     ...
;     f32x16 pA0, pA1, pB0, pB1; float dlA, dlB, alA, alB; v8i pa; const int NT = seq / 64;
;     const int NS = NT >> 1;
;     WBAR();
;     ISSUE(0);
;     WBAR();
;     if (1 < NS) ISSUE(1);
;     qkt(pA0, pA1, KSL(0), ka0, ka1, qf, negm); partialSM<true>(pA0, pA1, negm, dlA, alA);
.LBB0_586:
	v_lshrrev_b32_e32 v0, 2, v2
	v_bfe_u32 v2, v2, 2, 2
	v_lshlrev_b32_e32 v3, 1, v239
	v_bitop3_b32 v0, v3, v0, 3 bitop3:0x78
	v_bitop3_b32 v2, v3, v2, 1 bitop3:0x36
	v_lshlrev_b32_e32 v0, 4, v0
	v_lshlrev_b32_e32 v58, 4, v2
	v_mul_u32_u24_e32 v2, 0xc0, v238
	v_or_b32_e32 v244, v0, v2
	s_add_i32 m0, s15, 0
	v_or_b32_e32 v245, v58, v2
	global_load_lds_dwordx4 v4, s[0:1]
	v_add_u32_e32 v59, 0, v244
	v_add_u32_e32 v60, 0, v245
	ds_read_b128 v[2:5], v59 offset:49152
	ds_read_b128 v[6:9], v60 offset:49152
	v_readlane_b32 s68, v253, 62
	v_readlane_b32 s69, v253, 63
	v_readlane_b32 s70, v254, 0
	v_readlane_b32 s71, v254, 1
	v_readlane_b32 s72, v254, 2
	v_readlane_b32 s73, v254, 3
	v_readlane_b32 s74, v254, 4
	v_readlane_b32 s75, v254, 5
	v_readlane_b32 s76, v254, 6
	v_readlane_b32 s77, v254, 7
	v_readlane_b32 s78, v254, 8
	v_readlane_b32 s79, v254, 9
	v_readlane_b32 s80, v254, 10
	v_readlane_b32 s81, v254, 11
	v_readlane_b32 s82, v254, 12
	v_readlane_b32 s83, v254, 13
	s_mov_b32 s69, s68
	s_mov_b32 s70, s68
	s_mov_b32 s71, s68
	s_mov_b32 s72, s68
	s_mov_b32 s73, s68
	s_mov_b32 s74, s68
	s_mov_b32 s75, s68
	s_mov_b32 s76, s68
	s_mov_b32 s77, s68
	s_mov_b32 s78, s68
	s_mov_b32 s79, s68
	s_mov_b32 s80, s68
	s_mov_b32 s81, s68
	s_mov_b32 s82, s68
	s_mov_b32 s83, s68
	v_mov_b64_e32 v[18:19], s[68:69]
	v_mov_b64_e32 v[20:21], s[70:71]
	v_mov_b64_e32 v[22:23], s[72:73]
	v_mov_b64_e32 v[24:25], s[74:75]
	v_mov_b64_e32 v[26:27], s[76:77]
	v_mov_b64_e32 v[28:29], s[78:79]
	v_mov_b64_e32 v[30:31], s[80:81]
	v_mov_b64_e32 v[32:33], s[82:83]
	ds_read_b128 v[34:37], v59 offset:49216
	ds_read_b128 v[38:41], v60 offset:49216
	s_waitcnt vmcnt(0) lgkmcnt(0)
	v_mfma_scale_f32_32x32x64_f8f6f4 v[2:17], v[2:9], v[184:191], v[18:33], v234, v233 op_sel_hi:[0,0,0]
	ds_read_b128 v[46:49], v60 offset:55296
	ds_read_b128 v[42:45], v59 offset:55296
	ds_read_b128 v[50:53], v59 offset:49280
	ds_read_b128 v[54:57], v60 offset:49280
	s_mov_b32 s0, s68
	v_writelane_b32 v253, s0, 62
	s_lshl_b32 s28, s2, 13
	s_add_i32 s28, s28, s17
	v_writelane_b32 v254, s2, 0
	v_writelane_b32 v254, s3, 1
	v_writelane_b32 v254, s4, 2
	v_writelane_b32 v254, s5, 3
	v_writelane_b32 v254, s6, 4
	v_writelane_b32 v254, s7, 5
	v_writelane_b32 v254, s8, 6
	v_writelane_b32 v254, s9, 7
	v_writelane_b32 v254, s10, 8
	v_writelane_b32 v254, s11, 9
	s_waitcnt lgkmcnt(2)
	v_mfma_scale_f32_32x32x64_f8f6f4 v[18:33], v[42:49], v[184:191], v[18:33], v234, v233 op_sel_hi:[0,0,0]
	v_writelane_b32 v254, s12, 10
	v_writelane_b32 v254, s13, 11
	v_writelane_b32 v254, s14, 12
	v_writelane_b32 v254, s15, 13
	s_and_b32 s0, s14, 0x3fffffc0
	s_lshl_b32 s0, s0, 2
	s_add_i32 s20, s0, 0
	s_lshl_b32 s0, s2, 12
	s_lshl_b32 s35, s16, 13
	s_add_i32 s29, s28, s0
	s_add_i32 s35, s35, s19
	s_lshl_b32 s0, s16, 12
	s_lshl_b32 s26, s18, 13
	s_lshl_b32 s22, s2, 6
	s_add_i32 s2, s35, s0
	v_mfma_scale_f32_32x32x64_f8f6f4 v[2:17], v[34:41], v[176:183], v[2:17], v234, v233 op_sel_hi:[0,0,0]
	ds_read_b128 v[38:41], v60 offset:55360
	ds_read_b128 v[34:37], v59 offset:55360
	ds_read_b128 v[42:45], v59 offset:55424
	ds_read_b128 v[46:49], v60 offset:55424
	s_add_i32 s26, s26, s46
	s_lshl_b32 s0, s18, 12
	s_lshl_b32 s31, s33, 13
	s_add_i32 s20, s20, 0x18000
	s_add_i32 s27, s26, s0
	s_add_i32 s31, s31, s50
	s_lshl_b32 s0, s33, 12
	v_or_b32_e32 v246, 0x3800, v58
	v_or_b32_e32 v248, 0x3000, v58
	v_or_b32_e32 v249, 0x2800, v58
	v_or_b32_e32 v250, 0x2000, v58
	v_or_b32_e32 v251, 0x3800, v0
	v_or_b32_e32 v252, 0x3000, v0
	v_or_b32_e32 v231, 0x2800, v0
	s_waitcnt lgkmcnt(2)
	v_mfma_scale_f32_32x32x64_f8f6f4 v[18:33], v[34:41], v[176:183], v[18:33], v234, v233 op_sel_hi:[0,0,0]
	v_lshlrev_b32_e32 v34, 6, v238
	v_or_b32_e32 v240, v58, v34
	v_or_b32_e32 v241, v0, v34
	v_add_u32_e32 v247, 0, v34
	v_or_b32_e32 v218, 0x2000, v0
	v_mov_b32_e32 v0, v1
	v_writelane_b32 v253, s1, 63
	s_mov_b32 s21, 2
	s_lshr_b32 s47, s3, 6
	s_lshr_b32 s14, s3, 7
	s_mov_b32 s15, 0
	v_cmp_eq_u32_e64 s[12:13], 0, v239
	v_lshl_add_u32 v243, v238, 2, s20
	v_lshlrev_b32_e32 v242, 4, v239
	s_lshl_b32 s34, s16, 6
	v_mfma_scale_f32_32x32x64_f8f6f4 v[2:17], v[50:57], v[168:175], v[2:17], v234, v233 op_sel_hi:[0,0,0]
	s_lshl_b32 s3, s18, 6
	s_lshl_b32 s30, s33, 6
	s_add_i32 s49, s31, s0
	s_lshl_b32 s16, s42, 6
	s_add_i32 s18, s38, s51
	s_add_i32 s33, s39, s51
	s_mov_b32 s68, 0xfffe5000
	s_mov_b32 s69, 0xfffe6000
	s_mov_b32 s70, 0xfffe7000
	s_mov_b32 s71, 0xfffe8000
	s_mov_b32 s72, 0xfffe9000
	s_mov_b32 s73, 0xfffea000
	s_mov_b32 s74, 0xfffeb000
	s_mov_b32 s75, 0xfffec000
	s_mov_b32 s76, 0xfffed000
	s_waitcnt lgkmcnt(0)
; template <bool FIRST>
; __device__ __forceinline__ void partialSM(f32x16& p0, f32x16& p1, f32x16& negm, float& dl, float& alpha) {
;     float pmax = p0[0];
; #pragma unroll
;     for (int r = 1; r < 16; ++r) pmax = fmaxf(pmax, p0[r]);
; #pragma unroll
;     for (int r = 0; r < 16; ++r) pmax = fmaxf(pmax, p1[r]);
;     { auto rr = __builtin_amdgcn_permlane32_swap(__float_as_uint(pmax), __float_as_uint(pmax), false, false);
;       pmax = fmaxf(__uint_as_float(rr[0]), __uint_as_float(rr[1])); }
;     if (FIRST) {
;         dl = 0.f; alpha = 1.f; const float d0_ = pmax - SH;
; #pragma unroll
;         for (int r = 0; r < 16; ++r) { p0[r] -= d0_; p1[r] -= d0_; negm[r] -= d0_; }
;     } else {
;         const bool keep = __all(pmax <= SH + THRL);
;         dl = keep ? 0.f : fmaxf(pmax - SH, 0.f); alpha = __builtin_amdgcn_exp2f(-dl);
;     }
; #pragma unroll
;     for (int r = 0; r < 16; ++r) p0[r] = __builtin_amdgcn_exp2f(p0[r]);
; }
; __device__ __forceinline__ void attn_unit(const unsigned char* __restrict__ Qb, const unsigned char* __restrict__ Kh, const unsigned char* __restrict__ VTh, f16* __restrict__ Ob, int seq, LAS char* lds) {
;     ...
;     f32x16 o[5] = {}; v8i qf[3]; f32x16 negm;
; #pragma unroll
;     for (int r = 0; r < 16; ++r) negm[r] = SH;
	v_mfma_scale_f32_32x32x64_f8f6f4 v[18:33], v[42:49], v[168:175], v[18:33], v234, v233 op_sel_hi:[0,0,0]
	s_nop 2
	v_max_f32_e32 v35, v3, v3
	v_max_f32_e32 v36, v2, v2
	v_max_f32_e32 v35, v36, v35
	v_max3_f32 v35, v35, v4, v5
	v_max3_f32 v35, v35, v6, v7
	v_max3_f32 v35, v35, v8, v9
	v_max3_f32 v35, v35, v10, v11
	v_max3_f32 v35, v35, v12, v13
	v_max3_f32 v35, v35, v14, v15
	v_max3_f32 v35, v35, v16, v17
	s_mov_b32 s77, 0xfffee000
	s_mov_b32 s78, 0xfffef000
	s_mov_b32 s79, 0xffff0000
	s_mov_b32 s80, 0xffff1000
	s_mov_b32 s81, 0xffff2000
	s_nop 1
	v_max3_f32 v35, v35, v18, v19
	v_max3_f32 v35, v35, v20, v21
	v_max3_f32 v35, v35, v22, v23
	v_max3_f32 v35, v35, v24, v25
	v_max3_f32 v35, v35, v26, v27
	v_max3_f32 v35, v35, v28, v29
	v_max3_f32 v35, v35, v30, v31
	v_max3_f32 v35, v35, v32, v33
	v_mov_b32_e32 v36, v35
	s_nop 1
	v_permlane32_swap_b32_e32 v35, v36
	v_max_f32_e32 v36, v36, v36
	v_max_f32_e32 v35, v35, v35
	v_max_f32_e32 v35, v35, v36
	v_add_f32_e32 v35, -4.0, v35
	v_sub_f32_e32 v2, v2, v35
	v_exp_f32_e32 v228, v2
	v_sub_f32_e32 v2, v3, v35
	v_exp_f32_e32 v229, v2
	v_sub_f32_e32 v2, v4, v35
	v_exp_f32_e32 v220, v2
	v_sub_f32_e32 v2, v5, v35
	v_exp_f32_e32 v221, v2
	v_sub_f32_e32 v2, v6, v35
	v_exp_f32_e32 v226, v2
	v_sub_f32_e32 v2, v7, v35
	v_exp_f32_e32 v227, v2
	v_sub_f32_e32 v2, v8, v35
	v_exp_f32_e32 v224, v2
	v_sub_f32_e32 v2, v9, v35
	v_exp_f32_e32 v225, v2
	v_sub_f32_e32 v2, v10, v35
	v_exp_f32_e32 v222, v2
	v_sub_f32_e32 v2, v11, v35
	v_exp_f32_e32 v223, v2
	v_sub_f32_e32 v2, v12, v35
	v_exp_f32_e32 v162, v2
	v_sub_f32_e32 v2, v13, v35
	v_exp_f32_e32 v163, v2
	v_sub_f32_e32 v2, v14, v35
	v_exp_f32_e32 v166, v2
	v_sub_f32_e32 v2, v15, v35
	v_exp_f32_e32 v167, v2
	v_sub_f32_e32 v2, v16, v35
	v_exp_f32_e32 v164, v2
	v_sub_f32_e32 v2, v17, v35
	v_exp_f32_e32 v165, v2
	v_mov_b32_e32 v14, v1
	v_mov_b32_e32 v15, v1
	v_sub_f32_e32 v127, v33, v35
	v_sub_f32_e32 v126, v32, v35
	v_sub_f32_e32 v125, v31, v35
	v_sub_f32_e32 v124, v30, v35
	v_sub_f32_e32 v123, v29, v35
	v_sub_f32_e32 v122, v28, v35
	v_sub_f32_e32 v121, v27, v35
	v_sub_f32_e32 v120, v26, v35
	v_sub_f32_e32 v119, v25, v35
	v_sub_f32_e32 v118, v24, v35
	v_sub_f32_e32 v117, v23, v35
	v_sub_f32_e32 v116, v22, v35
	v_sub_f32_e32 v115, v21, v35
	v_sub_f32_e32 v114, v20, v35
	v_sub_f32_e32 v113, v19, v35
	v_sub_f32_e32 v112, v18, v35
	v_sub_f32_e32 v96, 4.0, v35
	v_mov_b32_e32 v2, v1
	v_mov_b32_e32 v3, v1
	v_mov_b32_e32 v4, v1
	v_mov_b32_e32 v5, v1
	v_mov_b32_e32 v6, v1
	v_mov_b32_e32 v7, v1
	v_mov_b32_e32 v8, v1
	v_mov_b32_e32 v9, v1
	v_mov_b32_e32 v10, v1
	v_mov_b32_e32 v11, v1
	v_mov_b32_e32 v12, v1
	v_mov_b32_e32 v13, v1
	v_mov_b64_e32 v[78:79], v[14:15]
	v_mov_b64_e32 v[62:63], v[14:15]
	v_mov_b64_e32 v[46:47], v[14:15]
	v_mov_b64_e32 v[30:31], v[14:15]
	v_mov_b64_e32 v[94:95], v[14:15]
	v_mov_b32_e32 v97, v96
	v_mov_b32_e32 v98, v96
	v_mov_b32_e32 v99, v96
	v_mov_b32_e32 v100, v96
	v_mov_b32_e32 v101, v96
	v_mov_b32_e32 v102, v96
	v_mov_b32_e32 v103, v96
	v_mov_b32_e32 v104, v96
	v_mov_b32_e32 v105, v96
	v_mov_b32_e32 v106, v96
	v_mov_b32_e32 v107, v96
	v_mov_b32_e32 v108, v96
	v_mov_b32_e32 v109, v96
	v_mov_b32_e32 v110, v96
	v_mov_b32_e32 v111, v96
	v_mov_b64_e32 v[76:77], v[12:13]
	v_mov_b64_e32 v[74:75], v[10:11]
	v_mov_b64_e32 v[72:73], v[8:9]
	v_mov_b64_e32 v[70:71], v[6:7]
	v_mov_b64_e32 v[68:69], v[4:5]
	v_mov_b64_e32 v[66:67], v[2:3]
	v_mov_b64_e32 v[64:65], v[0:1]
	v_mov_b64_e32 v[60:61], v[12:13]
	v_mov_b64_e32 v[58:59], v[10:11]
	v_mov_b64_e32 v[56:57], v[8:9]
	v_mov_b64_e32 v[54:55], v[6:7]
	v_mov_b64_e32 v[52:53], v[4:5]
	v_mov_b64_e32 v[50:51], v[2:3]
	v_mov_b64_e32 v[48:49], v[0:1]
	v_mov_b64_e32 v[44:45], v[12:13]
	v_mov_b64_e32 v[42:43], v[10:11]
	v_mov_b64_e32 v[40:41], v[8:9]
	v_mov_b64_e32 v[38:39], v[6:7]
	v_mov_b64_e32 v[36:37], v[4:5]
	v_mov_b64_e32 v[34:35], v[2:3]
	v_mov_b64_e32 v[32:33], v[0:1]
	v_mov_b64_e32 v[28:29], v[12:13]
	v_mov_b64_e32 v[26:27], v[10:11]
	v_mov_b64_e32 v[24:25], v[8:9]
	v_mov_b64_e32 v[22:23], v[6:7]
	v_mov_b64_e32 v[20:21], v[4:5]
	v_mov_b64_e32 v[18:19], v[2:3]
	v_mov_b64_e32 v[16:17], v[0:1]
	v_mov_b64_e32 v[92:93], v[12:13]
	v_mov_b64_e32 v[90:91], v[10:11]
	v_mov_b64_e32 v[88:89], v[8:9]
	v_mov_b64_e32 v[86:87], v[6:7]
	v_mov_b64_e32 v[84:85], v[4:5]
	v_mov_b64_e32 v[82:83], v[2:3]
	v_mov_b64_e32 v[80:81], v[0:1]
	v_lshlrev_b32_e32 v2, 4, v216
	v_and_b32_e32 v2, 0x3f0, v2
	v_or_b32_e32 v3, 0xffffe000, v2
	v_add_u32_e32 v4, s17, v3
	s_mov_b32 s0, 0xaaaaaaab
	v_mul_hi_u32 v5, v4, s0
	v_lshrrev_b32_e32 v6, 7, v5
	s_movk_i32 s0, 0xc0
	v_mul_lo_u32 v7, v6, s0
	v_add_u32_e32 v6, s22, v6
	s_movk_i32 s0, 0x300
	v_lshrrev_b32_e32 v5, 5, v5
	v_sub_u32_e32 v4, v4, v7
	v_mul_lo_u32 v6, v6, s0
	v_and_b32_e32 v5, 48, v5
	v_bitop3_b32 v4, v5, v6, v4 bitop3:0xde
	v_or_b32_e32 v8, s28, v2
	v_cndmask_b32_e64 v12, v8, v4, s[56:57]
	v_add_u32_e32 v4, s19, v3
	s_mov_b32 s0, 0xaaaaaaab
	v_mul_hi_u32 v5, v4, s0
	v_lshrrev_b32_e32 v6, 7, v5
	s_movk_i32 s0, 0xc0
	v_mul_lo_u32 v7, v6, s0
	v_add_u32_e32 v6, s34, v6
	s_movk_i32 s0, 0x300
	v_lshrrev_b32_e32 v5, 5, v5
	v_sub_u32_e32 v4, v4, v7
	v_mul_lo_u32 v6, v6, s0
	v_and_b32_e32 v5, 48, v5
	v_bitop3_b32 v4, v5, v6, v4 bitop3:0xde
	v_or_b32_e32 v8, s35, v2
	v_cndmask_b32_e64 v13, v4, v8, s[4:5]
	v_add_u32_e32 v4, s46, v3
	s_mov_b32 s0, 0xaaaaaaab
	v_mul_hi_u32 v5, v4, s0
	v_lshrrev_b32_e32 v6, 7, v5
	s_movk_i32 s0, 0xc0
	v_mul_lo_u32 v7, v6, s0
	v_add_u32_e32 v6, s3, v6
	s_movk_i32 s0, 0x300
	v_lshrrev_b32_e32 v5, 5, v5
	v_sub_u32_e32 v4, v4, v7
	v_mul_lo_u32 v6, v6, s0
	v_and_b32_e32 v5, 48, v5
	v_bitop3_b32 v4, v5, v6, v4 bitop3:0xde
	v_or_b32_e32 v8, s26, v2
	v_cndmask_b32_e64 v14, v4, v8, s[6:7]
	v_add_u32_e32 v4, s50, v3
	s_mov_b32 s0, 0xaaaaaaab
	v_mul_hi_u32 v5, v4, s0
	v_lshrrev_b32_e32 v6, 7, v5
	s_movk_i32 s0, 0xc0
	v_mul_lo_u32 v7, v6, s0
	v_add_u32_e32 v6, s30, v6
	s_movk_i32 s0, 0x300
	v_lshrrev_b32_e32 v5, 5, v5
	v_sub_u32_e32 v4, v4, v7
	v_mul_lo_u32 v6, v6, s0
	v_and_b32_e32 v5, 48, v5
	v_bitop3_b32 v4, v5, v6, v4 bitop3:0xde
	v_or_b32_e32 v8, s31, v2
	v_cndmask_b32_e64 v15, v4, v8, s[8:9]
	v_add_u32_e32 v4, s51, v3
	s_mov_b32 s0, 0xaaaaaaab
	v_mul_hi_u32 v5, v4, s0
	v_lshrrev_b32_e32 v6, 7, v5
	s_movk_i32 s0, 0xc0
	v_mul_lo_u32 v7, v6, s0
	v_add_u32_e32 v6, s16, v6
	s_movk_i32 s0, 0x300
	v_lshrrev_b32_e32 v5, 5, v5
	v_sub_u32_e32 v4, v4, v7
	v_mul_lo_u32 v6, v6, s0
	v_and_b32_e32 v5, 48, v5
	v_bitop3_b32 v4, v5, v6, v4 bitop3:0xde
	v_or_b32_e32 v8, s18, v2
	v_cndmask_b32_e64 v9, v4, v8, s[10:11]
	v_mov_b32_e32 v5, 0x19000
	v_lshl_add_u32 v246, v216, 4, v5
	v_lshl_add_u32 v248, v216, 2, v5
	ds_write_b128 v246, v[12:15]
	ds_write_b32 v248, v9 offset:8192
	s_bitcmp1_b32 s15, 0
	s_cselect_b32 s1, 0x6000, 0
	v_add_u32_e32 v12, s1, v244
	v_add_u32_e32 v13, s1, v245
	v_add_u32_e32 v14, 0xf000, v12
	v_add_u32_e32 v15, 0xf000, v13
	ds_read_b128 v[202:205], v12 offset:61440
	ds_read_b128 v[206:209], v13 offset:61440
	ds_read_b128 v[194:197], v14 offset:6144
	ds_read_b128 v[198:201], v15 offset:6144
	s_mov_b32 s82, 0xffff3000
	s_mov_b32 s83, 0xffff4000
	s_branch .LBB0_589

; #define LAS __attribute__((address_space(3)))
; template <bool FIRST>
; __device__ __forceinline__ void partialSM(f32x16& p0, f32x16& p1, f32x16& negm, float& dl, float& alpha) {
;     float pmax = p0[0];
; #pragma unroll
;     for (int r = 1; r < 16; ++r) pmax = fmaxf(pmax, p0[r]);
; #pragma unroll
;     for (int r = 0; r < 16; ++r) pmax = fmaxf(pmax, p1[r]);
;     { auto rr = __builtin_amdgcn_permlane32_swap(__float_as_uint(pmax), __float_as_uint(pmax), false, false);
;       pmax = fmaxf(__uint_as_float(rr[0]), __uint_as_float(rr[1])); }
;     if (FIRST) {
;         dl = 0.f; alpha = 1.f; const float d0_ = pmax - SH;
; #pragma unroll
;         for (int r = 0; r < 16; ++r) { p0[r] -= d0_; p1[r] -= d0_; negm[r] -= d0_; }
;     } else {
;         const bool keep = __all(pmax <= SH + THRL);
;         dl = keep ? 0.f : fmaxf(pmax - SH, 0.f); alpha = __builtin_amdgcn_exp2f(-dl);
;     }
; #pragma unroll
;     for (int r = 0; r < 16; ++r) p0[r] = __builtin_amdgcn_exp2f(p0[r]);
; }
; __device__ __forceinline__ void finishSM(f32x16& p0, f32x16& p1, v8i& pa) {
; #pragma unroll
;     for (int r = 0; r < 16; ++r) p1[r] = __builtin_amdgcn_exp2f(p1[r]);
; #pragma unroll
;     for (int w = 0; w < 4; ++w) { pa[w] = (int)pk4_fp8(p0[4 * w], p0[4 * w + 1], p0[4 * w + 2], p0[4 * w + 3]); pa[4 + w] = (int)pk4_fp8(p1[4 * w], p1[4 * w + 1], p1[4 * w + 2], p1[4 * w + 3]); }
; }
; __device__ __forceinline__ v8i ld32(const LAS char* a0, const LAS char* a1) { const v4i x = *(const LAS v4i*)a0, y = *(const LAS v4i*)a1; return (v8i){x[0], x[1], x[2], x[3], y[0], y[1], y[2], y[3]}; }
; __device__ __forceinline__ void qkt(f32x16& p0, f32x16& p1, const LAS char* Ks, int ka0, int ka1, const v8i* qf, const f32x16& negm) {
; #pragma unroll
;     for (int st = 0; st < 3; ++st) {
;         const v8i k0 = ld32(Ks + ka0 + 64 * st, Ks + ka1 + 64 * st), k1 = ld32(Ks + ka0 + 64 * st + 32 * 192, Ks + ka1 + 64 * st + 32 * 192);
;         if (st == 0) { p0 = MFMA8QK(k0, qf[st], negm); p1 = MFMA8QK(k1, qf[st], negm); }
;         else { p0 = MFMA8QK(k0, qf[st], p0); p1 = MFMA8QK(k1, qf[st], p1); } }
; }
; __device__ __forceinline__ void pv_d0(f32x16* o, const LAS char* Vs, int va0, int va1, v8i pa) {
; #pragma unroll
;     for (int d0 = 0; d0 < 4; ++d0) { const v8i vf = ld32(Vs + va0 + 2048 * d0, Vs + va1 + 2048 * d0); o[d0] = MFMA8(pa, vf, o[d0]); }
.LBB0_589:
	s_bitcmp1_b32 s15, 0
	s_cselect_b32 s0, 0x6000, 0
	s_add_i32 s0, s0, 0
	v_add_u32_e32 v0, s0, v244
	v_add_u32_e32 v210, s0, v245
	v_add_u32_e32 v211, 0xf000, v0
	v_add_u32_e32 v212, 0xf000, v210
	ds_read_b128 v[2:5], v0 offset:61504
	ds_read_b128 v[6:9], v210 offset:61504
	v_exp_f32_e32 v14, v116
	v_exp_f32_e32 v15, v117
	v_exp_f32_e32 v12, v114
	v_exp_f32_e32 v13, v115
	s_waitcnt lgkmcnt(4)
	v_mfma_scale_f32_32x32x64_f8f6f4 v[144:159], v[202:209], v[184:191], v[96:111], v234, v233 op_sel_hi:[0,0,0]
	ds_read_b128 v[202:205], v211 offset:6208
	ds_read_b128 v[206:209], v212 offset:6208
	v_exp_f32_e32 v114, v118
	v_exp_f32_e32 v115, v119
	v_exp_f32_e32 v119, v120
	v_exp_f32_e32 v120, v121
	v_cvt_pk_fp8_f32 v117, v14, v15
	v_exp_f32_e32 v10, v112
	v_exp_f32_e32 v11, v113
	s_waitcnt lgkmcnt(4)
	v_mfma_scale_f32_32x32x64_f8f6f4 v[128:143], v[194:201], v[184:191], v[96:111], v234, v233 op_sel_hi:[0,0,0]
	ds_read_b128 v[194:197], v0 offset:61568
	ds_read_b128 v[198:201], v210 offset:61568
	v_exp_f32_e32 v121, v122
	v_exp_f32_e32 v122, v123
	v_exp_f32_e32 v123, v124
	v_exp_f32_e32 v124, v125
	v_cvt_pk_fp8_f32 v117, v114, v115 op_sel:[0,0,1]
	v_cvt_pk_fp8_f32 v118, v119, v120
	v_exp_f32_e32 v125, v126
	s_waitcnt lgkmcnt(4)
	v_mfma_scale_f32_32x32x64_f8f6f4 v[144:159], v[2:9], v[176:183], v[144:159], v234, v233 op_sel_hi:[0,0,0]
	ds_read_b128 v[2:5], v211 offset:6272
	ds_read_b128 v[6:9], v212 offset:6272
	v_exp_f32_e32 v126, v127
	v_cvt_pk_fp8_f32 v112, v228, v229
	v_cvt_pk_fp8_f32 v116, v10, v11
	v_cvt_pk_fp8_f32 v113, v226, v227
	v_cvt_pk_fp8_f32 v114, v222, v223
	v_cvt_pk_fp8_f32 v115, v166, v167
	s_waitcnt lgkmcnt(4)
	v_mfma_scale_f32_32x32x64_f8f6f4 v[128:143], v[202:209], v[176:183], v[128:143], v234, v233 op_sel_hi:[0,0,0]
	v_cvt_pk_fp8_f32 v119, v123, v124
	v_cvt_pk_fp8_f32 v112, v220, v221 op_sel:[0,0,1]
	v_cvt_pk_fp8_f32 v116, v12, v13 op_sel:[0,0,1]
	v_cvt_pk_fp8_f32 v113, v224, v225 op_sel:[0,0,1]
	v_cvt_pk_fp8_f32 v114, v162, v163 op_sel:[0,0,1]
	v_cvt_pk_fp8_f32 v118, v121, v122 op_sel:[0,0,1]
	s_waitcnt lgkmcnt(2)
	v_mfma_scale_f32_32x32x64_f8f6f4 v[144:159], v[194:201], v[168:175], v[144:159], v234, v233 op_sel_hi:[0,0,0]
	v_cvt_pk_fp8_f32 v115, v164, v165 op_sel:[0,0,1]
	v_cvt_pk_fp8_f32 v119, v125, v126 op_sel:[0,0,1]
	v_mov_b32_e32 v161, v160
	v_mov_b32_e32 v162, v160
	v_mov_b32_e32 v163, v160
	s_waitcnt lgkmcnt(0)
	v_mfma_scale_f32_32x32x64_f8f6f4 v[128:143], v[2:9], v[168:175], v[128:143], v234, v233 op_sel_hi:[0,0,0]
	v_mov_b32_e32 v164, v160
	v_mov_b32_e32 v165, v160
	v_mov_b32_e32 v166, v160
	v_mov_b32_e32 v167, v160
	s_add_i32 s66, s21, -2
	s_ashr_i32 s38, s66, 1
	s_mul_hi_i32 s0, s38, 0x55555556
	s_lshr_b32 s1, s0, 31
	s_add_i32 s0, s0, s1
	s_mul_i32 s0, s0, 3
	s_sub_i32 s0, s38, s0
	s_lshl_b32 s0, s0, 14
	s_add_i32 s0, s0, 0
	v_add_u32_e32 v0, s0, v241
	v_add_u32_e32 v11, s0, v240
	ds_read_b128 v[208:211], v0
	ds_read_b128 v[212:215], v11
	ds_read_b128 v[200:203], v0 offset:2048
	ds_read_b128 v[204:207], v11 offset:2048
	ds_read_b128 v[192:195], v0 offset:4096
	ds_read_b128 v[196:199], v11 offset:4096
	ds_read_b128 v[2:5], v0 offset:6144
	ds_read_b128 v[6:9], v11 offset:6144
	ds_read_b128 v[120:123], v246
	ds_read_b32 v124, v248 offset:8192
	v_max_f32_e32 v0, v144, v145
	v_max3_f32 v0, v0, v146, v147
	v_max3_f32 v0, v0, v148, v149
	v_max3_f32 v0, v0, v150, v151
	v_max3_f32 v0, v0, v152, v153
	v_max3_f32 v0, v0, v154, v155
	v_max3_f32 v0, v0, v156, v157
	v_max3_f32 v0, v0, v158, v159
	s_waitcnt lgkmcnt(8)
	v_mfma_scale_f32_32x32x64_f8f6f4 v[64:79], v[112:119], v[208:215], v[64:79], v234, v234 op_sel_hi:[0,0,0]
	v_exp_f32_e32 v14, v144
	v_exp_f32_e32 v15, v145
	v_exp_f32_e32 v10, v148
	v_exp_f32_e32 v11, v149
	v_max3_f32 v0, v0, v128, v129
	v_max3_f32 v0, v0, v130, v131
	v_max3_f32 v0, v0, v132, v133
	v_max3_f32 v0, v0, v134, v135
	s_waitcnt lgkmcnt(6)
	v_mfma_scale_f32_32x32x64_f8f6f4 v[48:63], v[112:119], v[200:207], v[48:63], v234, v234 op_sel_hi:[0,0,0]
	v_exp_f32_e32 v12, v150
	v_exp_f32_e32 v13, v151
	v_max3_f32 v0, v0, v136, v137
	v_max3_f32 v0, v0, v138, v139
	v_max3_f32 v0, v0, v140, v141
	v_max3_f32 v0, v0, v142, v143
	s_waitcnt lgkmcnt(4)
	v_mfma_scale_f32_32x32x64_f8f6f4 v[32:47], v[112:119], v[192:199], v[32:47], v234, v234 op_sel_hi:[0,0,0]
	v_exp_f32_e32 v192, v146
	v_exp_f32_e32 v193, v147
	v_mov_b32_e32 v125, v0
	s_nop 1
	v_permlane32_swap_b32_e32 v0, v125
	s_waitcnt lgkmcnt(2)
	v_mfma_scale_f32_32x32x64_f8f6f4 v[16:31], v[112:119], v[2:9], v[16:31], v234, v234 op_sel_hi:[0,0,0]
	v_exp_f32_e32 v6, v152
	v_exp_f32_e32 v7, v153
	v_exp_f32_e32 v8, v154
	v_exp_f32_e32 v9, v155
	v_mfma_scale_f32_32x32x64_f8f6f4 v[80:95], v[112:119], v[160:167], v[80:95], v234, v234 op_sel_hi:[0,0,0]
	v_exp_f32_e32 v2, v156
	v_exp_f32_e32 v3, v157
	v_exp_f32_e32 v4, v158
	v_exp_f32_e32 v5, v159
	s_waitcnt vmcnt(0) lgkmcnt(0)
	s_barrier
	v_max_f32_e32 v0, v0, v125
	s_add_i32 s42, s38, 2
	v_cmp_ge_f32_e64 s[0:1], s67, v0
	s_cmp_ge_i32 s42, s14
	s_cbranch_scc1 .Lattn_noissue
	s_bitcmp1_b32 s21, 1
	s_cselect_b32 s44, 0x6000, 0
	v_add_u32_e32 v126, s44, v244
	v_add_u32_e32 v127, s44, v245
	ds_read_b128 v[208:211], v126 offset:49152
	ds_read_b128 v[212:215], v127 offset:49152
	s_ashr_i32 s43, s42, 31
	s_mul_i32 s38, s42, 0x18000
	s_mul_hi_i32 s39, s42, 0x18000
	s_add_u32 s38, s24, s38
	s_addc_u32 s39, s25, s39
	s_lshl_b64 s[40:41], s[42:43], 14
	s_add_u32 s40, s52, s40
	s_addc_u32 s41, s53, s41
	s_mul_hi_i32 s43, s42, 0x55555556
	s_lshr_b32 s67, s43, 31
	s_add_i32 s43, s43, s67
	s_mul_i32 s43, s43, 3
	s_sub_i32 s42, s42, s43
	s_lshl_b32 s67, s42, 14
	s_bitcmp1_b32 s66, 1
	s_mov_b32 s42, 0xa000
	s_cselect_b32 s66, 0x10000, s42
	s_and_b64 vcc, exec, s[6:7]
	s_cbranch_vccnz .Lattn_iss_hi
	s_add_i32 m0, s67, s28
	s_nop 0
	global_load_lds_dwordx4 v120, s[40:41]
	s_add_i32 m0, s2, s66
	s_nop 0
	global_load_lds_dwordx4 v121, s[38:39]
	s_add_i32 m0, s27, s66
	s_nop 0
	global_load_lds_dwordx4 v122, s[38:39]
	s_add_i32 m0, s67, s31
	s_nop 0
	global_load_lds_dwordx4 v123, s[40:41]
	s_add_i32 m0, s33, s66
	s_nop 0
	global_load_lds_dwordx4 v124, s[38:39]
	s_branch .Lattn_iss_done

; #define LAS __attribute__((address_space(3)))
; template <bool FIRST>
; __device__ __forceinline__ void partialSM(f32x16& p0, f32x16& p1, f32x16& negm, float& dl, float& alpha) {
;     float pmax = p0[0];
; #pragma unroll
;     for (int r = 1; r < 16; ++r) pmax = fmaxf(pmax, p0[r]);
; #pragma unroll
;     for (int r = 0; r < 16; ++r) pmax = fmaxf(pmax, p1[r]);
;     { auto rr = __builtin_amdgcn_permlane32_swap(__float_as_uint(pmax), __float_as_uint(pmax), false, false);
;       pmax = fmaxf(__uint_as_float(rr[0]), __uint_as_float(rr[1])); }
;     if (FIRST) {
;         dl = 0.f; alpha = 1.f; const float d0_ = pmax - SH;
; #pragma unroll
;         for (int r = 0; r < 16; ++r) { p0[r] -= d0_; p1[r] -= d0_; negm[r] -= d0_; }
;     } else {
;         const bool keep = __all(pmax <= SH + THRL);
;         dl = keep ? 0.f : fmaxf(pmax - SH, 0.f); alpha = __builtin_amdgcn_exp2f(-dl);
;     }
; #pragma unroll
;     for (int r = 0; r < 16; ++r) p0[r] = __builtin_amdgcn_exp2f(p0[r]);
; }
; __device__ __forceinline__ void finishSM(f32x16& p0, f32x16& p1, v8i& pa) {
; #pragma unroll
;     for (int r = 0; r < 16; ++r) p1[r] = __builtin_amdgcn_exp2f(p1[r]);
; #pragma unroll
;     for (int w = 0; w < 4; ++w) { pa[w] = (int)pk4_fp8(p0[4 * w], p0[4 * w + 1], p0[4 * w + 2], p0[4 * w + 3]); pa[4 + w] = (int)pk4_fp8(p1[4 * w], p1[4 * w + 1], p1[4 * w + 2], p1[4 * w + 3]); }
; }
; __device__ __forceinline__ v8i ld32(const LAS char* a0, const LAS char* a1) { const v4i x = *(const LAS v4i*)a0, y = *(const LAS v4i*)a1; return (v8i){x[0], x[1], x[2], x[3], y[0], y[1], y[2], y[3]}; }
; __device__ __forceinline__ void qkt(f32x16& p0, f32x16& p1, const LAS char* Ks, int ka0, int ka1, const v8i* qf, const f32x16& negm) {
; #pragma unroll
;     for (int st = 0; st < 3; ++st) {
;         const v8i k0 = ld32(Ks + ka0 + 64 * st, Ks + ka1 + 64 * st), k1 = ld32(Ks + ka0 + 64 * st + 32 * 192, Ks + ka1 + 64 * st + 32 * 192);
;         if (st == 0) { p0 = MFMA8QK(k0, qf[st], negm); p1 = MFMA8QK(k1, qf[st], negm); }
;         else { p0 = MFMA8QK(k0, qf[st], p0); p1 = MFMA8QK(k1, qf[st], p1); } }
; }
; __device__ __forceinline__ void pv_d0(f32x16* o, const LAS char* Vs, int va0, int va1, v8i pa) {
; #pragma unroll
;     for (int d0 = 0; d0 < 4; ++d0) { const v8i vf = ld32(Vs + va0 + 2048 * d0, Vs + va1 + 2048 * d0); o[d0] = MFMA8(pa, vf, o[d0]); }
.LBB0_615:
	s_mul_hi_u32 s0, s15, 0xaaaaaaab
	s_lshr_b32 s0, s0, 1
	s_mul_i32 s0, s0, 0xffff4000
	s_bfe_i32 s1, s21, 0x10001
	s_and_b32 s1, s1, 0x6000
	s_add_i32 s1, s1, 0
	v_add_u32_e32 v0, s1, v244
	v_add_u32_e32 v161, s1, v245
	ds_read_b128 v[194:197], v0 offset:55360
	ds_read_b128 v[198:201], v161 offset:55360
	v_exp_f32_e32 v129, v129
	v_exp_f32_e32 v162, v133
	s_waitcnt lgkmcnt(4)
	v_mfma_scale_f32_32x32x64_f8f6f4 v[144:159], v[208:215], v[184:191], v[96:111], v234, v233 op_sel_hi:[0,0,0]
	ds_read_b128 v[202:205], v0 offset:49216
	ds_read_b128 v[206:209], v161 offset:49216
	v_exp_f32_e32 v130, v130
	v_exp_f32_e32 v131, v131
	v_exp_f32_e32 v134, v134
	v_exp_f32_e32 v135, v135
	s_waitcnt lgkmcnt(4)
	v_mfma_scale_f32_32x32x64_f8f6f4 v[112:127], v[120:127], v[184:191], v[96:111], v234, v233 op_sel_hi:[0,0,0]
	v_exp_f32_e32 v136, v136
	v_exp_f32_e32 v137, v137
	v_exp_f32_e32 v140, v140
	v_exp_f32_e32 v141, v141
	s_waitcnt lgkmcnt(2)
	v_mfma_scale_f32_32x32x64_f8f6f4 v[112:127], v[194:201], v[176:183], v[112:127], v234, v233 op_sel_hi:[0,0,0]
	v_exp_f32_e32 v138, v138
	v_exp_f32_e32 v139, v139
	v_exp_f32_e32 v142, v142
	v_exp_f32_e32 v143, v143
	s_waitcnt lgkmcnt(0)
	v_mfma_scale_f32_32x32x64_f8f6f4 v[144:159], v[202:209], v[176:183], v[144:159], v234, v233 op_sel_hi:[0,0,0]
	ds_read_b128 v[194:197], v0 offset:55424
	ds_read_b128 v[198:201], v161 offset:55424
	ds_read_b128 v[202:205], v0 offset:49280
	ds_read_b128 v[206:209], v161 offset:49280
	v_exp_f32_e32 v0, v128
	v_exp_f32_e32 v161, v132
	v_cvt_pk_fp8_f32 v132, v0, v129
	v_cvt_pk_fp8_f32 v133, v161, v162
	v_cvt_pk_fp8_f32 v128, v14, v15
	v_cvt_pk_fp8_f32 v132, v130, v131 op_sel:[0,0,1]
	v_cvt_pk_fp8_f32 v133, v134, v135 op_sel:[0,0,1]
	s_waitcnt lgkmcnt(0)
	v_mfma_scale_f32_32x32x64_f8f6f4 v[112:127], v[194:201], v[168:175], v[112:127], v234, v233 op_sel_hi:[0,0,0]
	v_cvt_pk_fp8_f32 v129, v10, v11
	v_cvt_pk_fp8_f32 v130, v6, v7
	v_cvt_pk_fp8_f32 v134, v136, v137
	v_cvt_pk_fp8_f32 v131, v2, v3
	v_cvt_pk_fp8_f32 v135, v140, v141
	v_cvt_pk_fp8_f32 v128, v192, v193 op_sel:[0,0,1]
	v_cvt_pk_fp8_f32 v129, v12, v13 op_sel:[0,0,1]
	v_cvt_pk_fp8_f32 v130, v8, v9 op_sel:[0,0,1]
	v_cvt_pk_fp8_f32 v134, v138, v139 op_sel:[0,0,1]
	v_cvt_pk_fp8_f32 v131, v4, v5 op_sel:[0,0,1]
	v_cvt_pk_fp8_f32 v135, v142, v143 op_sel:[0,0,1]
	v_or_b32_e32 v10, s0, v218
	v_or_b32_e32 v11, s0, v250
	v_add_u32_e32 v10, v247, v10
	v_add_u32_e32 v11, v247, v11
	ds_read_b128 v[2:5], v10
	ds_read_b128 v[6:9], v11
	v_mfma_scale_f32_32x32x64_f8f6f4 v[144:159], v[202:209], v[168:175], v[144:159], v234, v233 op_sel_hi:[0,0,0]
	ds_read_b128 v[194:197], v10 offset:2048
	ds_read_b128 v[198:201], v11 offset:2048
	v_mov_b32_e32 v161, v160
	v_mov_b32_e32 v162, v160
	v_mov_b32_e32 v163, v160
	v_mov_b32_e32 v164, v160
	v_mov_b32_e32 v165, v160
	v_mov_b32_e32 v166, v160
	v_mov_b32_e32 v167, v160
	s_waitcnt lgkmcnt(2)
	v_mfma_scale_f32_32x32x64_f8f6f4 v[64:79], v[128:135], v[2:9], v[64:79], v234, v234 op_sel_hi:[0,0,0]
	ds_read_b128 v[2:5], v10 offset:4096
	ds_read_b128 v[6:9], v11 offset:4096
	s_waitcnt lgkmcnt(2)
	v_mfma_scale_f32_32x32x64_f8f6f4 v[48:63], v[128:135], v[194:201], v[48:63], v234, v234 op_sel_hi:[0,0,0]
	ds_read_b128 v[194:197], v10 offset:6144
	ds_read_b128 v[198:201], v11 offset:6144
	s_bitcmp0_b32 s15, 0
	s_cselect_b32 s1, 0x6000, 0
	v_add_u32_e32 v12, s1, v244
	v_add_u32_e32 v13, s1, v245
	v_add_u32_e32 v14, 0xf000, v12
	v_add_u32_e32 v15, 0xf000, v13
	v_exp_f32_e32 v228, v144
	v_exp_f32_e32 v229, v145
	v_exp_f32_e32 v220, v146
	v_exp_f32_e32 v221, v147
	v_exp_f32_e32 v226, v148
	s_waitcnt lgkmcnt(2)
	v_mfma_scale_f32_32x32x64_f8f6f4 v[32:47], v[128:135], v[2:9], v[32:47], v234, v234 op_sel_hi:[0,0,0]
	v_exp_f32_e32 v227, v149
	v_exp_f32_e32 v224, v150
	v_exp_f32_e32 v225, v151
	v_exp_f32_e32 v222, v152
	v_exp_f32_e32 v223, v153
	v_max_f32_e32 v0, v144, v145
	v_max3_f32 v0, v0, v146, v147
	v_max3_f32 v0, v0, v148, v149
	v_max3_f32 v0, v0, v150, v151
	v_max3_f32 v0, v0, v152, v153
	s_waitcnt lgkmcnt(0)
	v_mfma_scale_f32_32x32x64_f8f6f4 v[16:31], v[128:135], v[194:201], v[16:31], v234, v234 op_sel_hi:[0,0,0]
	ds_read_b128 v[202:205], v12 offset:61440
	ds_read_b128 v[206:209], v13 offset:61440
	ds_read_b128 v[194:197], v14 offset:6144
	ds_read_b128 v[198:201], v15 offset:6144
	v_max3_f32 v0, v0, v154, v155
	v_max3_f32 v0, v0, v156, v157
	v_max3_f32 v0, v0, v158, v159
	v_max3_f32 v0, v0, v112, v113
	v_max3_f32 v0, v0, v114, v115
	v_max3_f32 v0, v0, v116, v117
	v_max3_f32 v0, v0, v118, v119
	v_max3_f32 v0, v0, v120, v121
	v_max3_f32 v0, v0, v122, v123
	v_mfma_scale_f32_32x32x64_f8f6f4 v[80:95], v[128:135], v[160:167], v[80:95], v234, v234 op_sel_hi:[0,0,0]
	v_max3_f32 v0, v0, v124, v125
	v_max3_f32 v0, v0, v126, v127
	v_mov_b32_e32 v2, v0
	s_nop 1
	v_permlane32_swap_b32_e32 v0, v2
	v_max_f32_e32 v0, v0, v2
	v_cmp_ge_f32_e32 vcc, s67, v0
	v_exp_f32_e32 v162, v154
	s_cmp_lg_u64 vcc, exec
	v_exp_f32_e32 v163, v155
	v_exp_f32_e32 v166, v156
	v_exp_f32_e32 v167, v157
	v_exp_f32_e32 v164, v158
	v_exp_f32_e32 v165, v159
	s_cbranch_scc0 .LBB0_588
	v_add_f32_e32 v2, -4.0, v0
	v_max_f32_e32 v2, 0, v2
	v_exp_f32_e64 v0, -v2
	s_and_saveexec_b64 s[0:1], s[12:13]
	s_cbranch_execz .LBB0_587
	ds_write_b32 v243, v0 offset:128
	s_branch .LBB0_587
